# U GEMMs: XCD-aware unit order (4 channel tiles of a token tile on one XCD)
# speedup vs baseline: 1.0306x; 1.0058x over previous
.LBB0_271:
	s_and_b32 s98, s33, 7
	s_lshl_b32 s98, s98, 5
	s_lshr_b32 s99, s33, 3
	s_or_b32 s98, s98, s99
	s_cmp_eq_u32 s84, 0x100
	s_cselect_b32 s98, s98, s33
	s_add_u32 s31, s80, 0x600000
	s_addc_u32 s34, s81, 0
	s_ashr_i32 s35, s98, 2
	s_and_b32 s36, s98, 3
	s_cmpk_gt_i32 s98, 0x3ff
	v_readfirstlane_b32 s2, v164
	s_cbranch_scc1 .LBB0_287
	s_lshl_b32 s4, s35, 8
	s_lshl_b32 s5, s35, 1
	s_and_b32 s4, s4, 0xffffe000
	s_and_b32 s5, s5, 62
	s_or_b32 s4, s4, s5
	s_addk_i32 s4, 0x4000
	s_lshr_b32 s3, s2, 6
	s_ashr_i32 s5, s4, 31
	s_lshr_b32 s6, s2, 8
	s_lshl_b32 s37, s3, 10
	s_lshl_b32 s7, s36, 19
	s_lshl_b64 s[4:5], s[4:5], 11
	s_add_u32 s26, s28, s4
	s_addc_u32 s27, s29, s5
	s_waitcnt lgkmcnt(0)
	s_add_i32 s44, s37, 0
	v_mov_b32_e32 v143, 0
	v_lshl_or_b32 v140, v178, 17, v137
	s_add_i32 m0, s44, 0x10000
	v_mov_b32_e32 v141, v143
	v_lshl_or_b32 v138, v179, 17, v137
	v_lshl_add_u64 v[0:1], s[26:27], 0, v[140:141]
	global_load_lds_dwordx4 v140, s[26:27]
	s_add_i32 m0, s44, 0x12000
	s_mov_b64 s[4:5], 0x800
	global_load_lds_dwordx4 v138, s[26:27]
	s_add_i32 m0, s44, 0x14000
	v_lshl_add_u64 v[4:5], v[0:1], 0, s[4:5]
	v_mov_b32_e32 v139, v143
	global_load_lds_dwordx4 v[4:5], off
	s_add_i32 m0, s44, 0x16000
	v_lshl_add_u64 v[2:3], s[26:27], 0, v[138:139]
	s_add_u32 s24, s31, s7
	v_lshl_add_u64 v[4:5], v[2:3], 0, s[4:5]
	s_addc_u32 s25, s34, 0
	s_add_i32 s45, s44, 0x2000
	global_load_lds_dwordx4 v[4:5], off
	s_mov_b32 m0, s44
	s_add_u32 s8, s24, 0x40000
	global_load_lds_dwordx4 v128, s[24:25]
	s_mov_b32 m0, s45
	s_addc_u32 s9, s25, 0
	s_add_i32 s48, s44, 0x4000
	global_load_lds_dwordx4 v132, s[24:25]
	s_mov_b32 m0, s48
	s_add_i32 s49, s44, 0x6000
	global_load_lds_dwordx4 v128, s[8:9]
	s_mov_b32 m0, s49
	v_mov_b32_e32 v129, v143
	global_load_lds_dwordx4 v132, s[8:9]
	v_mov_b32_e32 v133, v143
	s_cmp_eq_u32 s6, 1
	s_mov_b32 s7, 0
	v_lshl_add_u64 v[4:5], s[24:25], 0, v[128:129]
	s_cselect_b64 s[8:9], -1, 0
	s_cmp_lg_u32 s6, 1
	v_lshl_add_u64 v[6:7], s[24:25], 0, v[132:133]
	s_cbranch_scc1 .LBB0_274
	s_barrier

.LBB0_277:
	s_add_i32 s66, s66, 1
	s_mul_i32 s2, s66, s53
	s_mul_hi_u32 s3, s66, s60
	s_add_i32 s3, s3, s2
	s_mul_i32 s2, s66, s60
	s_add_u32 s22, s2, s98
	s_addc_u32 s23, s3, s30
	v_cmp_gt_i64_e32 vcc, s[22:23], v[150:151]
	v_cmp_lt_i64_e64 s[2:3], s[22:23], v[148:149]
	s_lshr_b64 s[20:21], s[22:23], 2
	s_cbranch_vccnz .LBB0_279
	s_lshl_b32 s18, s20, 8
	s_lshl_b32 s19, s20, 1
	s_and_b32 s18, s18, 0xffffe000
	s_and_b32 s19, s19, 62
	s_or_b32 s18, s18, s19
	s_addk_i32 s18, 0x4000
	s_ashr_i32 s19, s18, 31
	s_lshl_b64 s[18:19], s[18:19], 11
	s_add_u32 s18, s28, s18
	s_addc_u32 s19, s29, s19

.LBB0_287:
	s_cmpk_gt_i32 s98, 0xff
	v_readfirstlane_b32 s2, v164
	s_cbranch_scc1 .LBB0_303
	s_lshl_b32 s6, s35, 8
	s_and_b32 s6, s6, 0xfffff000
	s_and_b32 s7, s98, 60
	s_or_b32 s6, s6, s7
	s_lshr_b32 s3, s2, 6
	v_and_or_b32 v0, v176, 32, v174
	v_lshrrev_b32_e32 v1, 2, v170
	s_ashr_i32 s7, s6, 31
	s_lshr_b32 s4, s2, 8
	s_lshl_b32 s26, s3, 10
	v_lshlrev_b32_e32 v0, 17, v0
	v_and_b32_e32 v1, 0x1800, v1
	s_lshl_b32 s5, s36, 19
	s_lshl_b64 s[6:7], s[6:7], 11
	v_or3_b32 v138, v0, v1, v137
	v_and_or_b32 v0, v175, 32, v174
	s_add_u32 s22, s28, s6
	v_lshlrev_b32_e32 v0, 17, v0
	v_and_b32_e32 v1, 0x800, v177
	s_addc_u32 s23, s29, s7
	s_add_i32 s27, s26, 0
	v_or3_b32 v140, v0, v1, v137
	s_add_i32 m0, s27, 0x10000
	v_mov_b32_e32 v143, 0
	global_load_lds_dwordx4 v140, s[22:23]
	s_add_i32 m0, s27, 0x12000
	s_add_u32 s6, s22, 0x1000
	global_load_lds_dwordx4 v138, s[22:23]
	s_addc_u32 s7, s23, 0
	s_add_i32 m0, s27, 0x14000
	v_mov_b32_e32 v141, v143
	global_load_lds_dwordx4 v140, s[6:7]
	s_add_i32 m0, s27, 0x16000
	s_add_u32 s20, s31, s5
	s_addc_u32 s21, s34, 0
	s_add_i32 s37, s27, 0x2000
	global_load_lds_dwordx4 v138, s[6:7]
	s_mov_b32 m0, s27
	s_add_u32 s6, s20, 0x40000
	global_load_lds_dwordx4 v128, s[20:21]
	s_mov_b32 m0, s37
	s_addc_u32 s7, s21, 0
	s_waitcnt lgkmcnt(0)
	s_add_i32 s44, s27, 0x4000
	global_load_lds_dwordx4 v132, s[20:21]
	s_mov_b32 m0, s44
	s_add_i32 s45, s27, 0x6000
	global_load_lds_dwordx4 v128, s[6:7]
	s_mov_b32 m0, s45
	v_mov_b32_e32 v139, v143
	global_load_lds_dwordx4 v132, s[6:7]
	v_mov_b32_e32 v129, v143
	v_mov_b32_e32 v133, v143
	s_cmp_eq_u32 s4, 1
	s_mov_b32 s5, 0
	v_lshl_add_u64 v[6:7], s[22:23], 0, v[140:141]
	v_lshl_add_u64 v[4:5], s[22:23], 0, v[138:139]
	v_lshl_add_u64 v[0:1], s[20:21], 0, v[128:129]
	s_cselect_b64 s[6:7], -1, 0
	s_cmp_lg_u32 s4, 1
	v_lshl_add_u64 v[2:3], s[20:21], 0, v[132:133]
	s_cbranch_scc1 .LBB0_290
	s_barrier

.LBB0_293:
	s_add_i32 s63, s63, 1
	s_mul_i32 s2, s63, s52
	s_mul_hi_u32 s3, s63, s53
	s_add_i32 s3, s3, s2
	s_mul_i32 s2, s63, s53
	s_add_u32 s18, s2, s98
	s_addc_u32 s19, s3, s30
	v_cmp_gt_i64_e32 vcc, s[18:19], v[150:151]
	v_cmp_lt_i64_e64 s[2:3], s[18:19], v[148:149]
	s_lshr_b64 s[16:17], s[18:19], 2
	s_cbranch_vccnz .LBB0_295
	s_lshl_b32 s14, s16, 8
	s_lshl_b32 s15, s16, 2
	s_and_b32 s14, s14, 0xfffff000
	s_and_b32 s15, s15, 60
	s_or_b32 s14, s15, s14
	s_ashr_i32 s15, s14, 31
	s_lshl_b64 s[14:15], s[14:15], 11
	s_add_u32 s14, s28, s14
	s_addc_u32 s15, s29, s15

	.amdhsa_kernel _Z8fwd_mega4Args
		.amdhsa_group_segment_fixed_size 0
		.amdhsa_private_segment_fixed_size 0
		.amdhsa_kernarg_size 432
		.amdhsa_user_sgpr_count 2
		.amdhsa_user_sgpr_dispatch_ptr 0
		.amdhsa_user_sgpr_queue_ptr 0
		.amdhsa_user_sgpr_kernarg_segment_ptr 1
		.amdhsa_user_sgpr_dispatch_id 0
		.amdhsa_user_sgpr_kernarg_preload_length 0
		.amdhsa_user_sgpr_kernarg_preload_offset 0
		.amdhsa_user_sgpr_private_segment_size 0
		.amdhsa_uses_dynamic_stack 0
		.amdhsa_enable_private_segment 0
		.amdhsa_system_sgpr_workgroup_id_x 1
		.amdhsa_system_sgpr_workgroup_id_y 0
		.amdhsa_system_sgpr_workgroup_id_z 0
		.amdhsa_system_sgpr_workgroup_info 0
		.amdhsa_system_vgpr_workitem_id 2
		.amdhsa_next_free_vgpr 253
		.amdhsa_next_free_sgpr 100
		.amdhsa_accum_offset 256
		.amdhsa_reserve_vcc 1
		.amdhsa_float_round_mode_32 0
		.amdhsa_float_round_mode_16_64 0
		.amdhsa_float_denorm_mode_32 3
		.amdhsa_float_denorm_mode_16_64 3
		.amdhsa_dx10_clamp 1
		.amdhsa_ieee_mode 1
		.amdhsa_fp16_overflow 0
		.amdhsa_tg_split 0
		.amdhsa_exception_fp_ieee_invalid_op 0
		.amdhsa_exception_fp_denorm_src 0
		.amdhsa_exception_fp_ieee_div_zero 0
		.amdhsa_exception_fp_ieee_overflow 0
		.amdhsa_exception_fp_ieee_underflow 0
		.amdhsa_exception_fp_ieee_inexact 0
		.amdhsa_exception_int_div_zero 0
	.end_amdhsa_kernel

amdhsa.kernels:
  - .agpr_count:     0
    .args:
      - .offset:         0
        .size:           176
        .value_kind:     by_value
      - .offset:         176
        .size:           4
        .value_kind:     hidden_block_count_x
      - .offset:         180
        .size:           4
        .value_kind:     hidden_block_count_y
      - .offset:         184
        .size:           4
        .value_kind:     hidden_block_count_z
      - .offset:         188
        .size:           2
        .value_kind:     hidden_group_size_x
      - .offset:         190
        .size:           2
        .value_kind:     hidden_group_size_y
      - .offset:         192
        .size:           2
        .value_kind:     hidden_group_size_z
      - .offset:         194
        .size:           2
        .value_kind:     hidden_remainder_x
      - .offset:         196
        .size:           2
        .value_kind:     hidden_remainder_y
      - .offset:         198
        .size:           2
        .value_kind:     hidden_remainder_z
      - .offset:         216
        .size:           8
        .value_kind:     hidden_global_offset_x
      - .offset:         224
        .size:           8
        .value_kind:     hidden_global_offset_y
      - .offset:         232
        .size:           8
        .value_kind:     hidden_global_offset_z
      - .offset:         240
        .size:           2
        .value_kind:     hidden_grid_dims
      - .offset:         264
        .size:           8
        .value_kind:     hidden_multigrid_sync_arg
      - .offset:         296
        .size:           4
        .value_kind:     hidden_dynamic_lds_size
    .group_segment_fixed_size: 0
    .kernarg_segment_align: 8
    .kernarg_segment_size: 432
    .language:       OpenCL C
    .language_version:
      - 2
      - 0
    .max_flat_workgroup_size: 512
    .name:           _Z8fwd_mega4Args
    .private_segment_fixed_size: 0
    .sgpr_count:     106
    .sgpr_spill_count: 3
    .symbol:         _Z8fwd_mega4Args.kd
    .uniform_work_group_size: 1
    .uses_dynamic_stack: false
    .vgpr_count:     253
    .vgpr_spill_count: 0
    .wavefront_size: 64
